# v19 + attention A/D branches: QK K-fragment LDS reads batched into free VGPRs, MFMAs back-to-back (bit-identical)
# baseline (speedup 1.0000x reference)
.LBB0_231:
	s_or_b64 exec, exec, s[8:9]
	v_lshl_add_u64 v[2:3], s[2:3], 1, v[120:121]
	global_load_dwordx4 v[2:5], v[2:3], off
	ds_read_b128 v[176:179], v137
	ds_read_b128 v[180:183], v137 offset:32
	ds_read_b128 v[184:187], v137 offset:64
	ds_read_b128 v[188:191], v137 offset:96
	ds_read_b128 v[192:195], v137 offset:128
	ds_read_b128 v[196:199], v137 offset:160
	ds_read_b128 v[200:203], v137 offset:6656
	ds_read_b128 v[204:207], v137 offset:6688
	ds_read_b128 v[208:211], v137 offset:6720
	ds_read_b128 v[212:215], v137 offset:6752
	ds_read_b128 v[234:237], v137 offset:6784
	ds_read_b128 v[246:249], v137 offset:6816
	s_waitcnt lgkmcnt(11)
	v_mfma_f32_32x32x16_bf16 v[48:63], v[176:179], v[80:83], 0
	s_waitcnt lgkmcnt(10)
	v_mfma_f32_32x32x16_bf16 v[48:63], v[180:183], v[84:87], v[48:63]
	s_waitcnt lgkmcnt(9)
	v_mfma_f32_32x32x16_bf16 v[48:63], v[184:187], v[88:91], v[48:63]
	s_waitcnt lgkmcnt(8)
	v_mfma_f32_32x32x16_bf16 v[48:63], v[188:191], v[92:95], v[48:63]
	s_waitcnt lgkmcnt(7)
	v_mfma_f32_32x32x16_bf16 v[48:63], v[192:195], v[96:99], v[48:63]
	s_waitcnt lgkmcnt(6)
	v_mfma_f32_32x32x16_bf16 v[48:63], v[196:199], v[100:103], v[48:63]
	s_waitcnt lgkmcnt(5)
	v_mfma_f32_32x32x16_bf16 v[64:79], v[200:203], v[80:83], 0
	s_waitcnt lgkmcnt(4)
	v_mfma_f32_32x32x16_bf16 v[64:79], v[204:207], v[84:87], v[64:79]
	s_waitcnt lgkmcnt(3)
	v_mfma_f32_32x32x16_bf16 v[64:79], v[208:211], v[88:91], v[64:79]
	s_waitcnt lgkmcnt(2)
	v_mfma_f32_32x32x16_bf16 v[64:79], v[212:215], v[92:95], v[64:79]
	s_waitcnt lgkmcnt(1)
	v_mfma_f32_32x32x16_bf16 v[64:79], v[234:237], v[96:99], v[64:79]
	s_waitcnt lgkmcnt(0)
	v_mfma_f32_32x32x16_bf16 v[64:79], v[246:249], v[100:103], v[64:79]
	v_max_f32_e32 v10, v49, v49
	v_max_f32_e32 v11, v50, v50
	v_max_f32_e32 v12, v51, v51
	s_nop 8
	v_max_f32_e32 v0, v65, v65
	v_max_f32_e32 v0, v10, v0
	v_max_f32_e32 v10, v66, v66
	v_max_f32_e32 v10, v11, v10
	v_max_f32_e32 v11, v67, v67
	v_max3_f32 v0, v48, v64, v0
	v_max_f32_e32 v11, v12, v11
	v_max3_f32 v0, v0, v10, v11
	v_max_f32_e32 v10, v68, v68
	v_max_f32_e32 v11, v52, v52
	v_max_f32_e32 v10, v11, v10
	v_max_f32_e32 v11, v69, v69
	v_max_f32_e32 v12, v53, v53
	v_max_f32_e32 v11, v12, v11
	v_max3_f32 v0, v0, v10, v11
	v_max_f32_e32 v10, v70, v70
	v_max_f32_e32 v11, v54, v54
	v_max_f32_e32 v10, v11, v10
	v_max_f32_e32 v11, v71, v71
	v_max_f32_e32 v12, v55, v55
	v_max_f32_e32 v11, v12, v11
	v_max3_f32 v0, v0, v10, v11
	v_max_f32_e32 v10, v72, v72
	v_max_f32_e32 v11, v56, v56
	v_max_f32_e32 v10, v11, v10
	v_max_f32_e32 v11, v73, v73
	v_max_f32_e32 v12, v57, v57
	v_max_f32_e32 v11, v12, v11
	v_max3_f32 v0, v0, v10, v11
	v_max_f32_e32 v10, v74, v74
	v_max_f32_e32 v11, v58, v58
	v_max_f32_e32 v10, v11, v10
	v_max_f32_e32 v11, v75, v75
	v_max_f32_e32 v12, v59, v59
	v_max_f32_e32 v11, v12, v11
	v_max3_f32 v0, v0, v10, v11
	v_max_f32_e32 v10, v76, v76
	v_max_f32_e32 v11, v60, v60
	v_max_f32_e32 v10, v11, v10
	v_max_f32_e32 v11, v77, v77
	v_max_f32_e32 v12, v61, v61
	v_max_f32_e32 v11, v12, v11
	v_max3_f32 v0, v0, v10, v11
	v_max_f32_e32 v10, v78, v78
	v_max_f32_e32 v11, v62, v62
	v_max_f32_e32 v10, v11, v10
	v_max_f32_e32 v11, v79, v79
	v_max_f32_e32 v12, v63, v63
	v_max_f32_e32 v11, v12, v11
	v_max3_f32 v0, v0, v10, v11
	v_sub_f32_e32 v10, v0, v142
	v_cmp_ge_f32_e32 vcc, s7, v10
	s_cmp_eq_u64 vcc, exec
	s_cbranch_scc1 .LBB0_233
	v_cmp_lt_i32_e32 vcc, v232, v226
	s_nop 1
	v_cndmask_b32_e32 v10, v224, v232, vcc
	v_lshlrev_b32_e32 v10, 2, v10
	ds_bpermute_b32 v10, v10, v0
	s_waitcnt lgkmcnt(0)
	v_max3_f32 v10, v142, v0, v10
	v_sub_f32_e32 v0, v142, v10
	v_exp_f32_e32 v0, v0
	v_mov_b32_e32 v142, v10
	v_mul_f32_e32 v143, v143, v0
	v_pk_mul_f32 v[46:47], v[46:47], v[0:1] op_sel_hi:[1,0]
	v_pk_mul_f32 v[44:45], v[44:45], v[0:1] op_sel_hi:[1,0]
	v_pk_mul_f32 v[42:43], v[42:43], v[0:1] op_sel_hi:[1,0]
	v_pk_mul_f32 v[40:41], v[40:41], v[0:1] op_sel_hi:[1,0]
	v_pk_mul_f32 v[38:39], v[38:39], v[0:1] op_sel_hi:[1,0]
	v_pk_mul_f32 v[36:37], v[36:37], v[0:1] op_sel_hi:[1,0]
	v_pk_mul_f32 v[34:35], v[34:35], v[0:1] op_sel_hi:[1,0]
	v_pk_mul_f32 v[32:33], v[32:33], v[0:1] op_sel_hi:[1,0]
	v_pk_mul_f32 v[30:31], v[30:31], v[0:1] op_sel_hi:[1,0]
	v_pk_mul_f32 v[28:29], v[28:29], v[0:1] op_sel_hi:[1,0]
	v_pk_mul_f32 v[26:27], v[26:27], v[0:1] op_sel_hi:[1,0]
	v_pk_mul_f32 v[24:25], v[24:25], v[0:1] op_sel_hi:[1,0]
	v_pk_mul_f32 v[22:23], v[22:23], v[0:1] op_sel_hi:[1,0]
	v_pk_mul_f32 v[20:21], v[20:21], v[0:1] op_sel_hi:[1,0]
	v_pk_mul_f32 v[18:19], v[18:19], v[0:1] op_sel_hi:[1,0]
	v_pk_mul_f32 v[16:17], v[16:17], v[0:1] op_sel_hi:[1,0]

.LBB0_237:
	s_or_b64 exec, exec, s[8:9]
	v_add_f32_e32 v0, v10, v0
	v_add_f32_e32 v0, 0, v0
	v_add_f32_e32 v10, v12, v11
	v_add_f32_e32 v0, v10, v0
	v_add_f32_e32 v10, v14, v13
	v_add_f32_e32 v0, v10, v0
	v_add_f32_e32 v10, v48, v15
	v_add_f32_e32 v0, v10, v0
	v_add_f32_e32 v10, v50, v49
	v_add_f32_e32 v0, v10, v0
	v_add_f32_e32 v10, v52, v51
	v_add_f32_e32 v0, v10, v0
	v_add_f32_e32 v10, v54, v53
	v_add_f32_e32 v0, v10, v0
	v_add_f32_e32 v10, v64, v55
	v_add_f32_e32 v0, v10, v0
	v_add_f32_e32 v10, v65, v56
	v_add_f32_e32 v0, v10, v0
	v_add_f32_e32 v10, v66, v57
	v_add_f32_e32 v0, v10, v0
	v_add_f32_e32 v10, v67, v58
	v_add_f32_e32 v0, v10, v0
	v_add_f32_e32 v10, v68, v59
	v_add_f32_e32 v0, v10, v0
	v_add_f32_e32 v10, v69, v60
	v_add_f32_e32 v0, v10, v0
	v_add_f32_e32 v10, v70, v61
	v_add_f32_e32 v0, v10, v0
	v_add_f32_e32 v10, v71, v62
	v_add_f32_e32 v0, v10, v0
	v_add_f32_e32 v10, v72, v63
	v_add_f32_e32 v0, v10, v0
	global_load_dwordx4 v[116:119], v[120:121], off offset:384
	v_add_f32_e32 v0, v143, v0
	ds_read_b128 v[176:179], v137 offset:22528
	ds_read_b128 v[180:183], v137 offset:22560
	ds_read_b128 v[184:187], v137 offset:22592
	ds_read_b128 v[188:191], v137 offset:22624
	ds_read_b128 v[192:195], v137 offset:22656
	ds_read_b128 v[196:199], v137 offset:22688
	ds_read_b128 v[200:203], v137 offset:29184
	ds_read_b128 v[204:207], v137 offset:29216
	ds_read_b128 v[208:211], v137 offset:29248
	ds_read_b128 v[212:215], v137 offset:29280
	ds_read_b128 v[234:237], v137 offset:29312
	ds_read_b128 v[246:249], v137 offset:29344
	s_waitcnt lgkmcnt(11)
	v_mfma_f32_32x32x16_bf16 v[48:63], v[176:179], v[80:83], 0
	s_waitcnt lgkmcnt(10)
	v_mfma_f32_32x32x16_bf16 v[48:63], v[180:183], v[84:87], v[48:63]
	s_waitcnt lgkmcnt(9)
	v_mfma_f32_32x32x16_bf16 v[48:63], v[184:187], v[88:91], v[48:63]
	s_waitcnt lgkmcnt(8)
	v_mfma_f32_32x32x16_bf16 v[48:63], v[188:191], v[92:95], v[48:63]
	s_waitcnt lgkmcnt(7)
	v_mfma_f32_32x32x16_bf16 v[48:63], v[192:195], v[96:99], v[48:63]
	s_waitcnt lgkmcnt(6)
	v_mfma_f32_32x32x16_bf16 v[48:63], v[196:199], v[100:103], v[48:63]
	s_waitcnt lgkmcnt(5)
	v_mfma_f32_32x32x16_bf16 v[64:79], v[200:203], v[80:83], 0
	s_waitcnt lgkmcnt(4)
	v_mfma_f32_32x32x16_bf16 v[64:79], v[204:207], v[84:87], v[64:79]
	s_waitcnt lgkmcnt(3)
	v_mfma_f32_32x32x16_bf16 v[64:79], v[208:211], v[88:91], v[64:79]
	s_waitcnt lgkmcnt(2)
	v_mfma_f32_32x32x16_bf16 v[64:79], v[212:215], v[92:95], v[64:79]
	s_waitcnt lgkmcnt(1)
	v_mfma_f32_32x32x16_bf16 v[64:79], v[234:237], v[96:99], v[64:79]
	s_waitcnt lgkmcnt(0)
	v_mfma_f32_32x32x16_bf16 v[64:79], v[246:249], v[100:103], v[64:79]
	v_max_f32_e32 v11, v49, v49
	v_max_f32_e32 v12, v50, v50
	v_max_f32_e32 v13, v51, v51
	s_nop 8
	v_max_f32_e32 v10, v65, v65
	v_max_f32_e32 v10, v11, v10
	v_max_f32_e32 v11, v66, v66
	v_max_f32_e32 v11, v12, v11
	v_max_f32_e32 v12, v67, v67
	v_max3_f32 v10, v48, v64, v10
	v_max_f32_e32 v12, v13, v12
	v_max3_f32 v10, v10, v11, v12
	v_max_f32_e32 v11, v68, v68
	v_max_f32_e32 v12, v52, v52
	v_max_f32_e32 v11, v12, v11
	v_max_f32_e32 v12, v69, v69
	v_max_f32_e32 v13, v53, v53
	v_max_f32_e32 v12, v13, v12
	v_max3_f32 v10, v10, v11, v12
	v_max_f32_e32 v11, v70, v70
	v_max_f32_e32 v12, v54, v54
	v_max_f32_e32 v11, v12, v11
	v_max_f32_e32 v12, v71, v71
	v_max_f32_e32 v13, v55, v55
	v_max_f32_e32 v12, v13, v12
	v_max3_f32 v10, v10, v11, v12
	v_max_f32_e32 v11, v72, v72
	v_max_f32_e32 v12, v56, v56
	v_max_f32_e32 v11, v12, v11
	v_max_f32_e32 v12, v73, v73
	v_max_f32_e32 v13, v57, v57
	v_max_f32_e32 v12, v13, v12
	v_max3_f32 v10, v10, v11, v12
	v_max_f32_e32 v11, v74, v74
	v_max_f32_e32 v12, v58, v58
	v_max_f32_e32 v11, v12, v11
	v_max_f32_e32 v12, v75, v75
	v_max_f32_e32 v13, v59, v59
	v_max_f32_e32 v12, v13, v12
	v_max3_f32 v10, v10, v11, v12
	v_max_f32_e32 v11, v76, v76
	v_max_f32_e32 v12, v60, v60
	v_max_f32_e32 v11, v12, v11
	v_max_f32_e32 v12, v77, v77
	v_max_f32_e32 v13, v61, v61
	v_max_f32_e32 v12, v13, v12
	v_max3_f32 v10, v10, v11, v12
	v_max_f32_e32 v11, v78, v78
	v_max_f32_e32 v12, v62, v62
	v_max_f32_e32 v11, v12, v11
	v_max_f32_e32 v12, v79, v79
	v_max_f32_e32 v13, v63, v63
	v_max_f32_e32 v12, v13, v12
	v_max3_f32 v10, v10, v11, v12
	v_sub_f32_e32 v11, v10, v142
	v_cmp_ge_f32_e32 vcc, s7, v11
	s_cmp_eq_u64 vcc, exec
	s_cbranch_scc1 .LBB0_239
	v_cmp_lt_i32_e32 vcc, v232, v226
	s_nop 1
	v_cndmask_b32_e32 v11, v224, v232, vcc
	v_lshlrev_b32_e32 v11, 2, v11
	ds_bpermute_b32 v11, v11, v10
	s_waitcnt lgkmcnt(0)
	v_max3_f32 v11, v142, v10, v11
	v_sub_f32_e32 v10, v142, v11
	v_exp_f32_e32 v10, v10
	v_mov_b32_e32 v142, v11
	v_mul_f32_e32 v0, v0, v10
	v_pk_mul_f32 v[46:47], v[46:47], v[10:11] op_sel_hi:[1,0]
	v_pk_mul_f32 v[44:45], v[44:45], v[10:11] op_sel_hi:[1,0]
	v_pk_mul_f32 v[42:43], v[42:43], v[10:11] op_sel_hi:[1,0]
	v_pk_mul_f32 v[40:41], v[40:41], v[10:11] op_sel_hi:[1,0]
	v_pk_mul_f32 v[38:39], v[38:39], v[10:11] op_sel_hi:[1,0]
	v_pk_mul_f32 v[36:37], v[36:37], v[10:11] op_sel_hi:[1,0]
	v_pk_mul_f32 v[34:35], v[34:35], v[10:11] op_sel_hi:[1,0]
	v_pk_mul_f32 v[32:33], v[32:33], v[10:11] op_sel_hi:[1,0]
	v_pk_mul_f32 v[30:31], v[30:31], v[10:11] op_sel_hi:[1,0]
	v_pk_mul_f32 v[28:29], v[28:29], v[10:11] op_sel_hi:[1,0]
	v_pk_mul_f32 v[26:27], v[26:27], v[10:11] op_sel_hi:[1,0]
	v_pk_mul_f32 v[24:25], v[24:25], v[10:11] op_sel_hi:[1,0]
	v_pk_mul_f32 v[22:23], v[22:23], v[10:11] op_sel_hi:[1,0]
	v_pk_mul_f32 v[20:21], v[20:21], v[10:11] op_sel_hi:[1,0]
	v_pk_mul_f32 v[18:19], v[18:19], v[10:11] op_sel_hi:[1,0]
	v_pk_mul_f32 v[16:17], v[16:17], v[10:11] op_sel_hi:[1,0]

.LBB0_262:
	v_add_u32_e32 v2, s2, v108
	v_ashrrev_i32_e32 v3, 31, v2
	v_lshlrev_b64 v[2:3], 8, v[2:3]
	v_lshl_add_u64 v[2:3], v[112:113], 0, v[2:3]
	v_lshl_add_u64 v[6:7], s[2:3], 1, v[110:111]
	v_add_u32_e32 v120, 0, v116
	global_load_dwordx4 v[2:5], v[2:3], off
	s_nop 0
	global_load_dwordx4 v[6:9], v[6:7], off
	ds_read_b128 v[176:179], v120
	ds_read_b128 v[180:183], v120 offset:32
	ds_read_b128 v[184:187], v120 offset:64
	ds_read_b128 v[188:191], v120 offset:96
	ds_read_b128 v[192:195], v120 offset:4608
	ds_read_b128 v[196:199], v120 offset:4640
	ds_read_b128 v[200:203], v120 offset:4672
	ds_read_b128 v[204:207], v120 offset:4704
	s_waitcnt lgkmcnt(7)
	v_mfma_f32_32x32x16_bf16 v[48:63], v[176:179], v[80:83], 0
	s_waitcnt lgkmcnt(6)
	v_mfma_f32_32x32x16_bf16 v[48:63], v[180:183], v[84:87], v[48:63]
	s_waitcnt lgkmcnt(5)
	v_mfma_f32_32x32x16_bf16 v[48:63], v[184:187], v[88:91], v[48:63]
	s_waitcnt lgkmcnt(4)
	v_mfma_f32_32x32x16_bf16 v[48:63], v[188:191], v[92:95], v[48:63]
	s_waitcnt lgkmcnt(3)
	v_mfma_f32_32x32x16_bf16 v[64:79], v[192:195], v[80:83], 0
	s_waitcnt lgkmcnt(2)
	v_mfma_f32_32x32x16_bf16 v[64:79], v[196:199], v[84:87], v[64:79]
	s_waitcnt lgkmcnt(1)
	v_mfma_f32_32x32x16_bf16 v[64:79], v[200:203], v[88:91], v[64:79]
	s_waitcnt lgkmcnt(0)
	v_mfma_f32_32x32x16_bf16 v[64:79], v[204:207], v[92:95], v[64:79]
	s_nop 3
	v_max_f32_e32 v10, v49, v49
	v_max_f32_e32 v11, v50, v50
	v_max_f32_e32 v12, v51, v51
	s_nop 8
	v_max_f32_e32 v0, v65, v65
	v_max_f32_e32 v0, v10, v0
	v_max_f32_e32 v10, v66, v66
	v_max_f32_e32 v10, v11, v10
	v_max_f32_e32 v11, v67, v67
	v_max3_f32 v0, v48, v64, v0
	v_max_f32_e32 v11, v12, v11
	v_max3_f32 v0, v0, v10, v11
	v_max_f32_e32 v10, v68, v68
	v_max_f32_e32 v11, v52, v52
	v_max_f32_e32 v10, v11, v10
	v_max_f32_e32 v11, v69, v69
	v_max_f32_e32 v12, v53, v53
	v_max_f32_e32 v11, v12, v11
	v_max3_f32 v0, v0, v10, v11
	v_max_f32_e32 v10, v70, v70
	v_max_f32_e32 v11, v54, v54
	v_max_f32_e32 v10, v11, v10
	v_max_f32_e32 v11, v71, v71
	v_max_f32_e32 v12, v55, v55
	v_max_f32_e32 v11, v12, v11
	v_max3_f32 v0, v0, v10, v11
	v_max_f32_e32 v10, v72, v72
	v_max_f32_e32 v11, v56, v56
	v_max_f32_e32 v10, v11, v10
	v_max_f32_e32 v11, v73, v73
	v_max_f32_e32 v12, v57, v57
	v_max_f32_e32 v11, v12, v11
	v_max3_f32 v0, v0, v10, v11
	v_max_f32_e32 v10, v74, v74
	v_max_f32_e32 v11, v58, v58
	v_max_f32_e32 v10, v11, v10
	v_max_f32_e32 v11, v75, v75
	v_max_f32_e32 v12, v59, v59
	v_max_f32_e32 v11, v12, v11
	v_max3_f32 v0, v0, v10, v11
	v_max_f32_e32 v10, v76, v76
	v_max_f32_e32 v11, v60, v60
	v_max_f32_e32 v10, v11, v10
	v_max_f32_e32 v11, v77, v77
	v_max_f32_e32 v12, v61, v61
	v_max_f32_e32 v11, v12, v11
	v_max3_f32 v0, v0, v10, v11
	v_max_f32_e32 v10, v78, v78
	v_max_f32_e32 v11, v62, v62
	v_max_f32_e32 v10, v11, v10
	v_max_f32_e32 v11, v79, v79
	v_max_f32_e32 v12, v63, v63
	v_max_f32_e32 v11, v12, v11
	v_max3_f32 v0, v0, v10, v11
	v_sub_f32_e32 v10, v0, v119
	v_cmp_ge_f32_e32 vcc, s7, v10
	s_cmp_eq_u64 vcc, exec
	s_cbranch_scc1 .LBB0_264
	v_cmp_lt_i32_e32 vcc, v232, v226
	s_nop 1
	v_cndmask_b32_e32 v10, v224, v232, vcc
	v_lshlrev_b32_e32 v10, 2, v10
	ds_bpermute_b32 v10, v10, v0
	s_waitcnt lgkmcnt(0)
	v_max3_f32 v10, v119, v0, v10
	v_sub_f32_e32 v0, v119, v10
	v_exp_f32_e32 v0, v0
	v_mov_b32_e32 v119, v10
	v_mul_f32_e32 v121, v121, v0
	v_pk_mul_f32 v[46:47], v[46:47], v[0:1] op_sel_hi:[1,0]
	v_pk_mul_f32 v[44:45], v[44:45], v[0:1] op_sel_hi:[1,0]
	v_pk_mul_f32 v[42:43], v[42:43], v[0:1] op_sel_hi:[1,0]
	v_pk_mul_f32 v[40:41], v[40:41], v[0:1] op_sel_hi:[1,0]
	v_pk_mul_f32 v[38:39], v[38:39], v[0:1] op_sel_hi:[1,0]
	v_pk_mul_f32 v[36:37], v[36:37], v[0:1] op_sel_hi:[1,0]
	v_pk_mul_f32 v[34:35], v[34:35], v[0:1] op_sel_hi:[1,0]
	v_pk_mul_f32 v[32:33], v[32:33], v[0:1] op_sel_hi:[1,0]
	v_pk_mul_f32 v[30:31], v[30:31], v[0:1] op_sel_hi:[1,0]
	v_pk_mul_f32 v[28:29], v[28:29], v[0:1] op_sel_hi:[1,0]
	v_pk_mul_f32 v[26:27], v[26:27], v[0:1] op_sel_hi:[1,0]
	v_pk_mul_f32 v[24:25], v[24:25], v[0:1] op_sel_hi:[1,0]
	v_pk_mul_f32 v[22:23], v[22:23], v[0:1] op_sel_hi:[1,0]
	v_pk_mul_f32 v[20:21], v[20:21], v[0:1] op_sel_hi:[1,0]
	v_pk_mul_f32 v[18:19], v[18:19], v[0:1] op_sel_hi:[1,0]
	v_pk_mul_f32 v[16:17], v[16:17], v[0:1] op_sel_hi:[1,0]
.LBB0_264:
	v_sub_f32_e32 v0, v48, v119
	v_exp_f32_e32 v122, v0
	v_sub_f32_e32 v0, v64, v119
	v_exp_f32_e32 v123, v0
	v_sub_f32_e32 v0, v49, v119
	v_sub_f32_e32 v10, v65, v119
	v_exp_f32_e32 v0, v0
	v_exp_f32_e32 v10, v10
	v_add_f32_e32 v11, v123, v122
	v_pk_add_f32 v[12:13], v[10:11], v[0:1]
	v_sub_f32_e32 v11, v50, v119
	v_exp_f32_e32 v124, v11
	v_sub_f32_e32 v11, v66, v119
	v_pk_add_f32 v[64:65], v[12:13], v[12:13] op_sel_hi:[0,1]
	v_exp_f32_e32 v125, v11
	v_sub_f32_e32 v11, v51, v119
	v_exp_f32_e32 v64, v11
	v_sub_f32_e32 v11, v67, v119
	v_exp_f32_e32 v12, v11
	v_add_f32_e32 v13, v125, v124
	v_sub_f32_e32 v11, v52, v119
	v_pk_add_f32 v[14:15], v[12:13], v[64:65]
	v_exp_f32_e32 v13, v11
	v_sub_f32_e32 v11, v68, v119
	v_pk_add_f32 v[66:67], v[14:15], v[14:15] op_sel_hi:[0,1]
	v_exp_f32_e32 v126, v11
	v_sub_f32_e32 v11, v53, v119
	v_exp_f32_e32 v66, v11
	v_sub_f32_e32 v11, v69, v119
	v_exp_f32_e32 v14, v11
	v_add_f32_e32 v15, v126, v13
	v_sub_f32_e32 v11, v54, v119
	v_pk_add_f32 v[48:49], v[14:15], v[66:67]
	v_exp_f32_e32 v15, v11
	v_sub_f32_e32 v11, v70, v119
	v_pk_add_f32 v[68:69], v[48:49], v[48:49] op_sel_hi:[0,1]
	v_exp_f32_e32 v127, v11
	v_sub_f32_e32 v11, v55, v119
	v_exp_f32_e32 v68, v11
	v_sub_f32_e32 v11, v71, v119
	v_exp_f32_e32 v48, v11
	v_add_f32_e32 v49, v127, v15
	v_sub_f32_e32 v11, v56, v119
	v_pk_add_f32 v[50:51], v[48:49], v[68:69]
	v_exp_f32_e32 v49, v11
	v_sub_f32_e32 v11, v72, v119
	v_pk_add_f32 v[70:71], v[50:51], v[50:51] op_sel_hi:[0,1]
	v_exp_f32_e32 v128, v11
	v_sub_f32_e32 v11, v57, v119
	v_exp_f32_e32 v70, v11
	v_sub_f32_e32 v11, v73, v119
	v_exp_f32_e32 v50, v11
	v_add_f32_e32 v51, v128, v49
	v_sub_f32_e32 v11, v58, v119
	v_pk_add_f32 v[52:53], v[50:51], v[70:71]
	v_exp_f32_e32 v51, v11
	v_sub_f32_e32 v11, v74, v119
	v_pk_add_f32 v[72:73], v[52:53], v[52:53] op_sel_hi:[0,1]
	v_exp_f32_e32 v71, v11
	v_sub_f32_e32 v11, v59, v119
	v_exp_f32_e32 v72, v11
	v_sub_f32_e32 v11, v75, v119
	v_exp_f32_e32 v52, v11
	v_add_f32_e32 v53, v71, v51
	v_sub_f32_e32 v11, v60, v119
	v_cvt_pk_bf16_f32 v60, v13, v66
	v_pk_add_f32 v[54:55], v[52:53], v[72:73]
	v_exp_f32_e32 v53, v11
	v_sub_f32_e32 v11, v76, v119
	v_pk_add_f32 v[74:75], v[54:55], v[54:55] op_sel_hi:[0,1]
	v_exp_f32_e32 v73, v11
	v_sub_f32_e32 v11, v61, v119
	v_exp_f32_e32 v74, v11
	v_sub_f32_e32 v11, v77, v119
	v_exp_f32_e32 v54, v11
	v_add_f32_e32 v55, v73, v53
	v_sub_f32_e32 v11, v62, v119
	v_cvt_pk_bf16_f32 v61, v15, v68
	v_pk_add_f32 v[56:57], v[54:55], v[74:75]
	v_exp_f32_e32 v55, v11
	v_sub_f32_e32 v11, v78, v119
	v_pk_add_f32 v[76:77], v[56:57], v[56:57] op_sel_hi:[0,1]
	v_exp_f32_e32 v75, v11
	v_sub_f32_e32 v11, v63, v119
	v_exp_f32_e32 v76, v11
	v_sub_f32_e32 v11, v79, v119
	v_exp_f32_e32 v56, v11
	v_add_f32_e32 v57, v75, v55
	v_pk_add_f32 v[58:59], v[56:57], v[76:77]
	s_nop 0
	v_add_f32_e32 v11, v58, v59
	v_cvt_pk_bf16_f32 v58, v122, v0
	v_add_u32_e32 v0, 0x2000, v117
	v_cvt_pk_bf16_f32 v59, v124, v64
	ds_read2_b64 v[62:65], v0 offset0:128 offset1:130
	v_add_u32_e32 v0, 0x3000, v118
	s_waitcnt lgkmcnt(0)
	v_mfma_f32_32x32x16_bf16 v[32:47], v[62:65], v[58:61], v[32:47]
	ds_read2_b64 v[62:65], v0 offset0:192 offset1:194
	v_add_f32_e32 v11, v121, v11
	s_waitcnt lgkmcnt(0)
	v_mfma_f32_32x32x16_bf16 v[16:31], v[62:65], v[58:61], v[16:31]
	v_cvt_pk_bf16_f32 v58, v49, v70
	v_add_u32_e32 v49, 0x2000, v118
	ds_read2_b64 v[62:65], v49 offset0:132 offset1:134
	ds_read2_b64 v[66:69], v49 offset0:136 offset1:138
	v_cvt_pk_bf16_f32 v59, v51, v72
	v_cvt_pk_bf16_f32 v60, v53, v74
	v_cvt_pk_bf16_f32 v61, v55, v76
	s_waitcnt lgkmcnt(1)
	s_nop 0
	v_mfma_f32_32x32x16_bf16 v[32:47], v[62:65], v[58:61], v[32:47]
	ds_read2_b64 v[62:65], v0 offset0:196 offset1:198
	s_waitcnt lgkmcnt(0)
	v_mfma_f32_32x32x16_bf16 v[16:31], v[62:65], v[58:61], v[16:31]
	v_cvt_pk_bf16_f32 v59, v125, v12
	v_cvt_pk_bf16_f32 v60, v126, v14
	ds_read2_b64 v[12:15], v0 offset0:200 offset1:202
	v_cvt_pk_bf16_f32 v58, v123, v10
	v_cvt_pk_bf16_f32 v61, v127, v48
	s_waitcnt lgkmcnt(0)
	s_nop 0
	v_mfma_f32_32x32x16_bf16 v[16:31], v[12:15], v[58:61], v[16:31]
	v_cvt_pk_bf16_f32 v12, v128, v50
	ds_read2_b64 v[48:51], v49 offset0:140 offset1:142
	v_cvt_pk_bf16_f32 v13, v71, v52
	v_cvt_pk_bf16_f32 v14, v73, v54
	v_cvt_pk_bf16_f32 v15, v75, v56
	v_mfma_f32_32x32x16_bf16 v[32:47], v[66:69], v[58:61], v[32:47]
	s_waitcnt lgkmcnt(0)
	v_mfma_f32_32x32x16_bf16 v[32:47], v[48:51], v[12:15], v[32:47]
	ds_read2_b64 v[48:51], v0 offset0:204 offset1:206
	s_waitcnt vmcnt(3)
	ds_write_b128 v107, v[96:99] offset:18432
	s_waitcnt vmcnt(2)
	ds_write_b128 v109, v[100:103] offset:27648
	s_waitcnt lgkmcnt(0)
	s_barrier
	global_load_dwordx4 v[96:99], v[114:115], off
	global_load_dwordx4 v[100:103], v[110:111], off offset:384
	s_waitcnt lgkmcnt(2)
	v_mfma_f32_32x32x16_bf16 v[16:31], v[48:51], v[12:15], v[16:31]
	ds_read_b128 v[176:179], v120 offset:18432
	ds_read_b128 v[180:183], v120 offset:18464
	ds_read_b128 v[184:187], v120 offset:18496
	ds_read_b128 v[188:191], v120 offset:18528
	ds_read_b128 v[192:195], v120 offset:23040
	ds_read_b128 v[196:199], v120 offset:23072
	ds_read_b128 v[200:203], v120 offset:23104
	ds_read_b128 v[204:207], v120 offset:23136
	s_waitcnt lgkmcnt(7)
	v_mfma_f32_32x32x16_bf16 v[64:79], v[176:179], v[80:83], 0
	s_waitcnt lgkmcnt(6)
	v_mfma_f32_32x32x16_bf16 v[64:79], v[180:183], v[84:87], v[64:79]
	s_waitcnt lgkmcnt(5)
	v_mfma_f32_32x32x16_bf16 v[64:79], v[184:187], v[88:91], v[64:79]
	s_waitcnt lgkmcnt(4)
	v_mfma_f32_32x32x16_bf16 v[64:79], v[188:191], v[92:95], v[64:79]
	s_waitcnt lgkmcnt(3)
	v_mfma_f32_32x32x16_bf16 v[48:63], v[192:195], v[80:83], 0
	s_waitcnt lgkmcnt(2)
	v_mfma_f32_32x32x16_bf16 v[48:63], v[196:199], v[84:87], v[48:63]
	s_waitcnt lgkmcnt(1)
	v_mfma_f32_32x32x16_bf16 v[48:63], v[200:203], v[88:91], v[48:63]
	s_waitcnt lgkmcnt(0)
	v_mfma_f32_32x32x16_bf16 v[48:63], v[204:207], v[92:95], v[48:63]
	s_nop 3
	v_max_f32_e32 v10, v65, v65
	v_max_f32_e32 v12, v66, v66
	v_max_f32_e32 v13, v67, v67
	s_nop 9
	v_max_f32_e32 v0, v49, v49
	v_max_f32_e32 v0, v10, v0
	v_max_f32_e32 v10, v50, v50
	v_max_f32_e32 v10, v12, v10
	v_max_f32_e32 v12, v51, v51
	v_max3_f32 v0, v64, v48, v0
	v_max_f32_e32 v12, v13, v12
	v_max3_f32 v0, v0, v10, v12
	v_max_f32_e32 v10, v52, v52
	v_max_f32_e32 v12, v68, v68
	v_max_f32_e32 v10, v12, v10
	v_max_f32_e32 v12, v53, v53
	v_max_f32_e32 v13, v69, v69
	v_max_f32_e32 v12, v13, v12
	v_max3_f32 v0, v0, v10, v12
	v_max_f32_e32 v10, v54, v54
	v_max_f32_e32 v12, v70, v70
	v_max_f32_e32 v10, v12, v10
	v_max_f32_e32 v12, v55, v55
	v_max_f32_e32 v13, v71, v71
	v_max_f32_e32 v12, v13, v12
	v_max3_f32 v0, v0, v10, v12
	v_max_f32_e32 v10, v56, v56
	v_max_f32_e32 v12, v72, v72
	v_max_f32_e32 v10, v12, v10
	v_max_f32_e32 v12, v57, v57
	v_max_f32_e32 v13, v73, v73
	v_max_f32_e32 v12, v13, v12
	v_max3_f32 v0, v0, v10, v12
	v_max_f32_e32 v10, v58, v58
	v_max_f32_e32 v12, v74, v74
	v_max_f32_e32 v10, v12, v10
	v_max_f32_e32 v12, v59, v59
	v_max_f32_e32 v13, v75, v75
	v_max_f32_e32 v12, v13, v12
	v_max3_f32 v0, v0, v10, v12
	v_max_f32_e32 v10, v60, v60
	v_max_f32_e32 v12, v76, v76
	v_max_f32_e32 v10, v12, v10
	v_max_f32_e32 v12, v61, v61
	v_max_f32_e32 v13, v77, v77
	v_max_f32_e32 v12, v13, v12
	v_max3_f32 v0, v0, v10, v12
	v_max_f32_e32 v10, v62, v62
	v_max_f32_e32 v12, v78, v78
	v_max_f32_e32 v10, v12, v10
	v_max_f32_e32 v12, v63, v63
	v_max_f32_e32 v13, v79, v79
	v_max_f32_e32 v12, v13, v12
	v_max3_f32 v0, v0, v10, v12
	v_sub_f32_e32 v10, v0, v119
	v_cmp_ge_f32_e32 vcc, s7, v10
	s_cmp_eq_u64 vcc, exec
	s_cbranch_scc1 .LBB0_261
	v_cmp_lt_i32_e32 vcc, v232, v226
	s_nop 1
	v_cndmask_b32_e32 v10, v224, v232, vcc
	v_lshlrev_b32_e32 v10, 2, v10
	ds_bpermute_b32 v10, v10, v0
	s_waitcnt lgkmcnt(0)
	v_max3_f32 v10, v119, v0, v10
	v_sub_f32_e32 v0, v119, v10
	v_exp_f32_e32 v0, v0
	v_mov_b32_e32 v119, v10
	v_mul_f32_e32 v11, v11, v0
	v_pk_mul_f32 v[46:47], v[46:47], v[0:1] op_sel_hi:[1,0]
	v_pk_mul_f32 v[44:45], v[44:45], v[0:1] op_sel_hi:[1,0]
	v_pk_mul_f32 v[42:43], v[42:43], v[0:1] op_sel_hi:[1,0]
	v_pk_mul_f32 v[40:41], v[40:41], v[0:1] op_sel_hi:[1,0]
	v_pk_mul_f32 v[38:39], v[38:39], v[0:1] op_sel_hi:[1,0]
	v_pk_mul_f32 v[36:37], v[36:37], v[0:1] op_sel_hi:[1,0]
	v_pk_mul_f32 v[34:35], v[34:35], v[0:1] op_sel_hi:[1,0]
	v_pk_mul_f32 v[32:33], v[32:33], v[0:1] op_sel_hi:[1,0]
	v_pk_mul_f32 v[30:31], v[30:31], v[0:1] op_sel_hi:[1,0]
	v_pk_mul_f32 v[28:29], v[28:29], v[0:1] op_sel_hi:[1,0]
	v_pk_mul_f32 v[26:27], v[26:27], v[0:1] op_sel_hi:[1,0]
	v_pk_mul_f32 v[24:25], v[24:25], v[0:1] op_sel_hi:[1,0]
	v_pk_mul_f32 v[22:23], v[22:23], v[0:1] op_sel_hi:[1,0]
	v_pk_mul_f32 v[20:21], v[20:21], v[0:1] op_sel_hi:[1,0]
	v_pk_mul_f32 v[18:19], v[18:19], v[0:1] op_sel_hi:[1,0]
	v_pk_mul_f32 v[16:17], v[16:17], v[0:1] op_sel_hi:[1,0]
	s_branch .LBB0_261
